# p4new_pl + nt (streaming) hint on P0 read-once x row loads
# speedup vs baseline: 1.0040x; 1.0040x over previous
; #define GAS __attribute__((address_space(1)))
; #define LAS __attribute__((address_space(3)))
; __global__ void __launch_bounds__(NWAVES * 64, 2) fwd(Args args) {
;     ...
;         f32x4 wreg[8][4];
; #pragma unroll
;         for (int c = 0; c < 8; ++c)
; #pragma unroll
;             for (int j = 0; j < 4; ++j) wreg[c][j] = *(const LAS f32x4*)(w8 + c * 1024 + 256 * j + 4 * lane);
;         f32x4 vn[4];
;         if (gw < M) { const GAS f32x4* xr0 = (const GAS f32x4*)(x + (size_t)gw * D) + 2 * lane;
; #pragma unroll
;             for (int j = 0; j < 4; ++j) vn[j] = xr0[128 * (j >> 1) + (j & 1)]; }
;     ...
;                 else { const int h = cc - 4; const float z = a1 + dt_bias[h]; const float sp = z > 20.f ? z : log1pf(expf(z)); r = -expf(A_log[h]) * sp; }
.LBB0_50:
	s_or_b64 exec, exec, s[6:7]
	s_cmpk_lt_i32 s40, 0x4000
	s_waitcnt lgkmcnt(0)
	s_barrier
	s_cbranch_scc0 .LBB0_65
	s_ashr_i32 s41, s40, 31
	s_lshl_b64 s[6:7], s[40:41], 12
	s_add_u32 s8, s16, s6
	s_addc_u32 s9, s17, s7
	v_lshlrev_b32_e32 v38, 5, v234
	global_load_dwordx4 v[146:149], v38, s[8:9] nt
	global_load_dwordx4 v[154:157], v38, s[8:9] offset:16 nt
	global_load_dwordx4 v[150:153], v38, s[8:9] offset:2048 nt
	global_load_dwordx4 v[158:161], v38, s[8:9] offset:2064 nt
	v_mov_b32_e32 v39, 0
	v_lshl_add_u64 v[162:163], s[16:17], 0, v[38:39]
	s_lshl_b64 s[16:17], s[40:41], 5
	s_add_u32 s16, s60, s16
	v_mov_b32_e32 v35, v39
	s_addc_u32 s17, s61, s17
	v_lshl_add_u64 v[34:35], s[16:17], 0, v[34:35]
	s_mov_b64 s[16:17], 0x100000
	s_ashr_i32 s43, s42, 31
	v_and_b32_e32 v1, 32, v0
	v_lshl_add_u64 v[168:169], v[34:35], 0, s[16:17]
	s_lshl_b64 s[16:17], s[42:43], 5
	s_lshl_b64 s[20:21], s[40:41], 11
	v_cmp_eq_u32_e64 s[6:7], 0, v1
	v_and_b32_e32 v1, 16, v0
	s_add_u32 s20, s60, s20
	v_lshlrev_b32_e32 v36, 4, v234
	v_cmp_eq_u32_e64 s[8:9], 0, v1
	v_and_b32_e32 v1, 8, v0
	v_mov_b32_e32 v37, v39
	s_addc_u32 s21, s61, s21
	v_cmp_eq_u32_e64 s[10:11], 0, v1
	v_add_u32_e32 v2, -4, v8
	v_mov_b32_e32 v3, v39
	v_add_u32_e32 v1, 0, v36
	v_lshl_add_u64 v[34:35], s[20:21], 0, v[36:37]
	s_mov_b64 s[20:21], 0x4000400
	v_lshlrev_b64 v[2:3], 2, v[2:3]
	v_add_u32_e32 v126, 0x12000, v1
	v_lshl_add_u64 v[170:171], v[34:35], 0, s[20:21]
	v_cmp_eq_u32_e64 s[12:13], 0, v4
	v_lshl_add_u64 v[164:165], s[28:29], 0, v[2:3]
	v_lshl_add_u64 v[166:167], s[26:27], 0, v[2:3]
	ds_read_b128 v[2:5], v126 offset:31744
	ds_read_b128 v[6:9], v126 offset:30720
	ds_read_b128 v[10:13], v126 offset:29696
	ds_read_b128 v[14:17], v126 offset:28672
	ds_read_b128 v[18:21], v126 offset:27648
	ds_read_b128 v[22:25], v126 offset:26624
	ds_read_b128 v[26:29], v126 offset:25600
	ds_read_b128 v[30:33], v126 offset:24576
	ds_read_b128 v[34:37], v126 offset:23552
	ds_read_b128 v[38:41], v126 offset:22528
	ds_read_b128 v[42:45], v126 offset:21504
	ds_read_b128 v[46:49], v126 offset:20480
	ds_read_b128 v[50:53], v126 offset:19456
	ds_read_b128 v[54:57], v126 offset:18432
	ds_read_b128 v[58:61], v126 offset:17408
	ds_read_b128 v[62:65], v126 offset:16384
	ds_read_b128 v[66:69], v126 offset:15360
	ds_read_b128 v[70:73], v126 offset:14336
	ds_read_b128 v[74:77], v126 offset:13312
	ds_read_b128 v[78:81], v126 offset:12288
	ds_read_b128 v[82:85], v126 offset:11264
	ds_read_b128 v[86:89], v126 offset:10240
	ds_read_b128 v[90:93], v126 offset:9216
	ds_read_b128 v[94:97], v126 offset:8192
	ds_read_b128 v[98:101], v126 offset:7168
	ds_read_b128 v[102:105], v126 offset:6144
	ds_read_b128 v[106:109], v126 offset:5120
	ds_read_b128 v[110:113], v126 offset:4096
	ds_read_b128 v[114:117], v126 offset:3072
	ds_read_b128 v[118:121], v126 offset:2048
	ds_read_b128 v[122:125], v126 offset:1024
	ds_read_b128 v[126:129], v126
	v_mbcnt_lo_u32_b32 v1, -1, 0
	v_cmp_lt_u32_e64 s[14:15], 31, v234
	s_lshl_b64 s[20:21], s[42:43], 11
	v_mbcnt_hi_u32_b32 v1, -1, v1
	s_mov_b32 s3, 0x41a00000
	s_mov_b32 s4, 0x3fb8aa3b
	s_mov_b32 s33, 0xc2ce8ed0
	s_mov_b32 s35, 0x42b17218
	s_mov_b32 s36, 0x7f800000
	s_mov_b32 s37, 0x3f2aaaab
	v_mov_b32_e32 v174, 0x3ecc95a3
	s_mov_b32 s43, 0x3f317218
	s_mov_b32 s48, 0x33800000
	s_mov_b32 s49, 0xbfb8aa3b
	s_mov_b32 s50, 0x42ce8ed0
	s_mov_b32 s51, 0xc2b17218
	v_mov_b32_e32 v175, 0x7f800000
	v_mov_b32_e32 v172, 0x3f317218
	s_mov_b64 s[44:45], exec
	s_and_b64 exec, exec, s[14:15]
	global_load_dword v241, v[164:165], off
	global_load_dword v242, v[166:167], off
	s_mov_b64 exec, s[44:45]
	s_branch .LBB0_54

; #define GAS __attribute__((address_space(1)))
; __global__ void __launch_bounds__(NWAVES * 64, 2) fwd(Args args) {
;     ...
;             if (m + NGW < M) { const GAS f32x4* xr = (const GAS f32x4*)(x + (size_t)(m + NGW) * D) + 2 * lane;
; #pragma unroll
;                 for (int j = 0; j < 4; ++j) vn[j] = xr[128 * (j >> 1) + (j & 1)]; }
.LBB0_54:
	s_add_i32 s40, s40, s42
	s_cmpk_gt_i32 s40, 0x3fff
	s_cselect_b64 s[26:27], -1, 0
	s_cmpk_lt_i32 s40, 0x4000
	s_cbranch_scc0 .LBB0_56
	s_ashr_i32 s41, s40, 31
	s_lshl_b64 s[28:29], s[40:41], 12
	v_lshl_add_u64 v[142:143], v[162:163], 0, s[28:29]
	global_load_dwordx4 v[130:133], v[142:143], off nt
	global_load_dwordx4 v[134:137], v[142:143], off offset:16 nt
	global_load_dwordx4 v[138:141], v[142:143], off offset:2048 nt
	s_nop 0
	global_load_dwordx4 v[142:145], v[142:143], off offset:2064 nt
	s_branch .LBB0_57
